# k9 plus: prologue weight transposes with gain folding issue the four row loads and four gain loads of an iteration together (one wait) instead of serial load/gain/wait per row group
# speedup vs baseline: 1.0115x; 1.0115x over previous
; #define GAS __attribute__((address_space(1)))
; #define LAS __attribute__((address_space(3)))
; __device__ __forceinline__ void tr_item(const float* W, int K, int N, const float* gain, bf16* WT, int k0, int n0, int dstrow, LAS float* scr, int lane, float f8s) {
;     ...
;     for (int i = 0; i < 16; ++i) { const int kk = 4 * i + r0; f32x4 v = *(const GAS f32x4*)(W + (size_t)(k0 + kk) * N + n0 + 4 * c4); if (gain) v = v * gain[k0 + kk];
;         *(LAS f32x4*)(scr + kk * 64 + 4 * (c4 ^ (2 * ((kk >> 3) & 7)))) = v; }
.LBB0_90:
	s_add_i32 s4, s4, 16
	v_add_u32_e32 v14, 0x1000, v14
	v_lshl_add_u64 v[62:63], v[62:63], 0, s[50:51]
	v_lshl_add_u64 v[64:65], v[64:65], 0, s[50:51]
	v_lshl_add_u64 v[66:67], v[66:67], 0, s[50:51]
	v_lshl_add_u64 v[68:69], v[68:69], 0, 64
	v_lshl_add_u64 v[70:71], v[70:71], 0, s[50:51]
	s_cmp_lg_u32 s4, 64
	v_lshl_add_u64 v[72:73], v[72:73], 0, 64
	s_cbranch_scc0 .LBB0_99
.LBB0_91:
	v_lshl_add_u64 v[130:131], v[64:65], 0, v[36:37]
	global_load_dwordx4 v[140:143], v[130:131], off
	v_lshl_add_u64 v[130:131], v[70:71], 0, v[36:37]
	global_load_dwordx4 v[144:147], v[130:131], off
	v_lshl_add_u64 v[130:131], v[66:67], 0, v[36:37]
	global_load_dwordx4 v[148:151], v[130:131], off
	v_lshl_add_u64 v[130:131], v[62:63], 0, v[36:37]
	global_load_dwordx4 v[152:155], v[130:131], off
	v_cndmask_b32_e64 v2, 0, 1, s[6:7]
	v_cmp_ne_u32_e64 s[0:1], 1, v2
	v_add_u32_e32 v136, s4, v12
	v_bitop3_b32 v132, v136, v11, 56 bitop3:0x6c
	v_lshl_add_u32 v132, v132, 2, v14
	v_add_u32_e32 v133, 4, v136
	v_bitop3_b32 v133, v133, v11, 56 bitop3:0x6c
	v_lshl_add_u32 v133, v133, 2, v14
	v_add_u32_e32 v134, 8, v136
	v_bitop3_b32 v134, v134, v11, 56 bitop3:0x6c
	v_lshl_add_u32 v134, v134, 2, v14
	v_add_u32_e32 v135, 12, v136
	v_bitop3_b32 v135, v135, v11, 56 bitop3:0x6c
	v_lshl_add_u32 v135, v135, 2, v14
	s_andn2_b64 vcc, exec, s[6:7]
	s_cbranch_vccnz .Ltrg1_nog
	global_load_dword v156, v[68:69], off
	global_load_dword v158, v[72:73], off
	global_load_dword v160, v[72:73], off offset:16
	global_load_dword v162, v[72:73], off offset:32
	s_waitcnt vmcnt(0)
	v_pk_mul_f32 v[142:143], v[142:143], v[156:157] op_sel_hi:[1,0]
	v_pk_mul_f32 v[140:141], v[140:141], v[156:157] op_sel_hi:[1,0]
	v_pk_mul_f32 v[146:147], v[146:147], v[158:159] op_sel_hi:[1,0]
	v_pk_mul_f32 v[144:145], v[144:145], v[158:159] op_sel_hi:[1,0]
	v_pk_mul_f32 v[150:151], v[150:151], v[160:161] op_sel_hi:[1,0]
	v_pk_mul_f32 v[148:149], v[148:149], v[160:161] op_sel_hi:[1,0]
	v_pk_mul_f32 v[154:155], v[154:155], v[162:163] op_sel_hi:[1,0]
	v_pk_mul_f32 v[152:153], v[152:153], v[162:163] op_sel_hi:[1,0]
	s_branch .Ltrg1_wr

; #define GAS __attribute__((address_space(1)))
; #define LAS __attribute__((address_space(3)))
; __device__ __forceinline__ void tr_item(const float* W, int K, int N, const float* gain, bf16* WT, int k0, int n0, int dstrow, LAS float* scr, int lane, float f8s) {
;     ...
;     for (int i = 0; i < 16; ++i) { const int kk = 4 * i + r0; f32x4 v = *(const GAS f32x4*)(W + (size_t)(k0 + kk) * N + n0 + 4 * c4); if (gain) v = v * gain[k0 + kk];
;         *(LAS f32x4*)(scr + kk * 64 + 4 * (c4 ^ (2 * ((kk >> 3) & 7)))) = v; }
.Ltrg1_wr:
	ds_write_b128 v132, v[140:143]
	ds_write_b128 v133, v[144:147] offset:1024
	ds_write_b128 v134, v[148:151] offset:2048
	ds_write_b128 v135, v[152:155] offset:3072
	s_branch .LBB0_90

; #define GAS __attribute__((address_space(1)))
; #define LAS __attribute__((address_space(3)))
; __device__ __forceinline__ void tr_item(const float* W, int K, int N, const float* gain, bf16* WT, int k0, int n0, int dstrow, LAS float* scr, int lane, float f8s) {
;     ...
;     for (int i = 0; i < 16; ++i) { const int kk = 4 * i + r0; f32x4 v = *(const GAS f32x4*)(W + (size_t)(k0 + kk) * N + n0 + 4 * c4); if (gain) v = v * gain[k0 + kk];
;         *(LAS f32x4*)(scr + kk * 64 + 4 * (c4 ^ (2 * ((kk >> 3) & 7)))) = v; }
.LBB0_108:
	s_add_i32 s17, s17, 16
	v_add_u32_e32 v14, 0x1000, v14
	v_lshl_add_u64 v[62:63], v[62:63], 0, s[56:57]
	v_lshl_add_u64 v[64:65], v[64:65], 0, s[56:57]
	v_lshl_add_u64 v[66:67], v[66:67], 0, s[56:57]
	v_lshl_add_u64 v[68:69], v[68:69], 0, 64
	s_cmp_lg_u32 s17, 64
	v_lshl_add_u64 v[70:71], v[70:71], 0, s[56:57]
	s_cbranch_scc0 .LBB0_117
.LBB0_109:
	v_lshl_add_u64 v[130:131], v[64:65], 0, s[4:5]
	global_load_dwordx4 v[140:143], v[130:131], off
	v_lshl_add_u64 v[130:131], v[70:71], 0, s[4:5]
	global_load_dwordx4 v[144:147], v[130:131], off
	v_lshl_add_u64 v[130:131], v[66:67], 0, s[4:5]
	global_load_dwordx4 v[148:151], v[130:131], off
	v_lshl_add_u64 v[130:131], v[62:63], 0, s[4:5]
	global_load_dwordx4 v[152:155], v[130:131], off
	v_cndmask_b32_e64 v2, 0, 1, s[18:19]
	v_cmp_ne_u32_e64 s[0:1], 1, v2
	v_add_u32_e32 v136, s17, v12
	v_bitop3_b32 v132, v136, v11, 56 bitop3:0x6c
	v_lshl_add_u32 v132, v132, 2, v14
	v_add_u32_e32 v133, 4, v136
	v_bitop3_b32 v133, v133, v11, 56 bitop3:0x6c
	v_lshl_add_u32 v133, v133, 2, v14
	v_add_u32_e32 v134, 8, v136
	v_bitop3_b32 v134, v134, v11, 56 bitop3:0x6c
	v_lshl_add_u32 v134, v134, 2, v14
	v_add_u32_e32 v135, 12, v136
	v_bitop3_b32 v135, v135, v11, 56 bitop3:0x6c
	v_lshl_add_u32 v135, v135, 2, v14
	s_andn2_b64 vcc, exec, s[18:19]
	s_cbranch_vccnz .Ltrg2_nog
	global_load_dword v156, v[68:69], off offset:-32
	global_load_dword v158, v[68:69], off offset:-16
	global_load_dword v160, v[68:69], off
	global_load_dword v162, v[68:69], off offset:16
	s_waitcnt vmcnt(0)
	v_pk_mul_f32 v[142:143], v[142:143], v[156:157] op_sel_hi:[1,0]
	v_pk_mul_f32 v[140:141], v[140:141], v[156:157] op_sel_hi:[1,0]
	v_pk_mul_f32 v[146:147], v[146:147], v[158:159] op_sel_hi:[1,0]
	v_pk_mul_f32 v[144:145], v[144:145], v[158:159] op_sel_hi:[1,0]
	v_pk_mul_f32 v[150:151], v[150:151], v[160:161] op_sel_hi:[1,0]
	v_pk_mul_f32 v[148:149], v[148:149], v[160:161] op_sel_hi:[1,0]
	v_pk_mul_f32 v[154:155], v[154:155], v[162:163] op_sel_hi:[1,0]
	v_pk_mul_f32 v[152:153], v[152:153], v[162:163] op_sel_hi:[1,0]
	s_branch .Ltrg2_wr

; #define GAS __attribute__((address_space(1)))
; #define LAS __attribute__((address_space(3)))
; __device__ __forceinline__ void tr_item(const float* W, int K, int N, const float* gain, bf16* WT, int k0, int n0, int dstrow, LAS float* scr, int lane, float f8s) {
;     ...
;     for (int i = 0; i < 16; ++i) { const int kk = 4 * i + r0; f32x4 v = *(const GAS f32x4*)(W + (size_t)(k0 + kk) * N + n0 + 4 * c4); if (gain) v = v * gain[k0 + kk];
;         *(LAS f32x4*)(scr + kk * 64 + 4 * (c4 ^ (2 * ((kk >> 3) & 7)))) = v; }
.LBB0_135:
	v_lshl_add_u64 v[130:131], v[64:65], 0, v[36:37]
	global_load_dwordx4 v[140:143], v[130:131], off
	v_lshl_add_u64 v[130:131], v[70:71], 0, v[36:37]
	global_load_dwordx4 v[144:147], v[130:131], off
	v_lshl_add_u64 v[130:131], v[66:67], 0, v[36:37]
	global_load_dwordx4 v[148:151], v[130:131], off
	v_lshl_add_u64 v[130:131], v[62:63], 0, v[36:37]
	global_load_dwordx4 v[152:155], v[130:131], off
	v_cndmask_b32_e64 v2, 0, 1, s[8:9]
	v_cmp_ne_u32_e64 s[0:1], 1, v2
	v_add_u32_e32 v136, s4, v12
	v_bitop3_b32 v132, v136, v11, 56 bitop3:0x6c
	v_lshl_add_u32 v132, v132, 2, v14
	v_add_u32_e32 v133, 4, v136
	v_bitop3_b32 v133, v133, v11, 56 bitop3:0x6c
	v_lshl_add_u32 v133, v133, 2, v14
	v_add_u32_e32 v134, 8, v136
	v_bitop3_b32 v134, v134, v11, 56 bitop3:0x6c
	v_lshl_add_u32 v134, v134, 2, v14
	v_add_u32_e32 v135, 12, v136
	v_bitop3_b32 v135, v135, v11, 56 bitop3:0x6c
	v_lshl_add_u32 v135, v135, 2, v14
	s_andn2_b64 vcc, exec, s[8:9]
	s_cbranch_vccnz .Ltrg4_nog
	global_load_dword v156, v[68:69], off
	global_load_dword v158, v[72:73], off
	global_load_dword v160, v[72:73], off offset:16
	global_load_dword v162, v[72:73], off offset:32
	s_waitcnt vmcnt(0)
	v_pk_mul_f32 v[142:143], v[142:143], v[156:157] op_sel_hi:[1,0]
	v_pk_mul_f32 v[140:141], v[140:141], v[156:157] op_sel_hi:[1,0]
	v_pk_mul_f32 v[146:147], v[146:147], v[158:159] op_sel_hi:[1,0]
	v_pk_mul_f32 v[144:145], v[144:145], v[158:159] op_sel_hi:[1,0]
	v_pk_mul_f32 v[150:151], v[150:151], v[160:161] op_sel_hi:[1,0]
	v_pk_mul_f32 v[148:149], v[148:149], v[160:161] op_sel_hi:[1,0]
	v_pk_mul_f32 v[154:155], v[154:155], v[162:163] op_sel_hi:[1,0]
	v_pk_mul_f32 v[152:153], v[152:153], v[162:163] op_sel_hi:[1,0]
	s_branch .Ltrg4_wr

; #define GAS __attribute__((address_space(1)))
; #define LAS __attribute__((address_space(3)))
; __device__ __forceinline__ void tr_item(const float* W, int K, int N, const float* gain, bf16* WT, int k0, int n0, int dstrow, LAS float* scr, int lane, float f8s) {
;     ...
;     for (int i = 0; i < 16; ++i) { const int kk = 4 * i + r0; f32x4 v = *(const GAS f32x4*)(W + (size_t)(k0 + kk) * N + n0 + 4 * c4); if (gain) v = v * gain[k0 + kk];
;         *(LAS f32x4*)(scr + kk * 64 + 4 * (c4 ^ (2 * ((kk >> 3) & 7)))) = v; }
.LBB0_152:
	s_add_i32 s4, s4, 16
	v_add_u32_e32 v14, 0x1000, v14
	v_lshl_add_u64 v[62:63], v[62:63], 0, s[78:79]
	v_lshl_add_u64 v[64:65], v[64:65], 0, s[78:79]
	v_lshl_add_u64 v[66:67], v[66:67], 0, s[78:79]
	v_lshl_add_u64 v[68:69], v[68:69], 0, 64
	v_lshl_add_u64 v[70:71], v[70:71], 0, s[78:79]
	s_cmp_lg_u32 s4, 64
	v_lshl_add_u64 v[72:73], v[72:73], 0, 64
	s_cbranch_scc0 .LBB0_161
.LBB0_153:
	v_lshl_add_u64 v[130:131], v[64:65], 0, v[36:37]
	global_load_dwordx4 v[140:143], v[130:131], off
	v_lshl_add_u64 v[130:131], v[70:71], 0, v[36:37]
	global_load_dwordx4 v[144:147], v[130:131], off
	v_lshl_add_u64 v[130:131], v[66:67], 0, v[36:37]
	global_load_dwordx4 v[148:151], v[130:131], off
	v_lshl_add_u64 v[130:131], v[62:63], 0, v[36:37]
	global_load_dwordx4 v[152:155], v[130:131], off
	v_cndmask_b32_e64 v2, 0, 1, s[28:29]
	v_cmp_ne_u32_e64 s[0:1], 1, v2
	v_add_u32_e32 v136, s4, v12
	v_bitop3_b32 v132, v136, v11, 56 bitop3:0x6c
	v_lshl_add_u32 v132, v132, 2, v14
	v_add_u32_e32 v133, 4, v136
	v_bitop3_b32 v133, v133, v11, 56 bitop3:0x6c
	v_lshl_add_u32 v133, v133, 2, v14
	v_add_u32_e32 v134, 8, v136
	v_bitop3_b32 v134, v134, v11, 56 bitop3:0x6c
	v_lshl_add_u32 v134, v134, 2, v14
	v_add_u32_e32 v135, 12, v136
	v_bitop3_b32 v135, v135, v11, 56 bitop3:0x6c
	v_lshl_add_u32 v135, v135, 2, v14
	s_andn2_b64 vcc, exec, s[28:29]
	s_cbranch_vccnz .Ltrg5_nog
	global_load_dword v156, v[68:69], off
	global_load_dword v158, v[72:73], off
	global_load_dword v160, v[72:73], off offset:16
	global_load_dword v162, v[72:73], off offset:32
	s_waitcnt vmcnt(0)
	v_pk_mul_f32 v[142:143], v[142:143], v[156:157] op_sel_hi:[1,0]
	v_pk_mul_f32 v[140:141], v[140:141], v[156:157] op_sel_hi:[1,0]
	v_pk_mul_f32 v[146:147], v[146:147], v[158:159] op_sel_hi:[1,0]
	v_pk_mul_f32 v[144:145], v[144:145], v[158:159] op_sel_hi:[1,0]
	v_pk_mul_f32 v[150:151], v[150:151], v[160:161] op_sel_hi:[1,0]
	v_pk_mul_f32 v[148:149], v[148:149], v[160:161] op_sel_hi:[1,0]
	v_pk_mul_f32 v[154:155], v[154:155], v[162:163] op_sel_hi:[1,0]
	v_pk_mul_f32 v[152:153], v[152:153], v[162:163] op_sel_hi:[1,0]
	s_branch .Ltrg5_wr

; #define GAS __attribute__((address_space(1)))
; #define LAS __attribute__((address_space(3)))
; __device__ __forceinline__ void tr_item(const float* W, int K, int N, const float* gain, bf16* WT, int k0, int n0, int dstrow, LAS float* scr, int lane, float f8s) {
;     const int c4 = lane & 15, r0 = lane >> 4;
; #pragma unroll 4
;     for (int i = 0; i < 16; ++i) { const int kk = 4 * i + r0; f32x4 v = *(const GAS f32x4*)(W + (size_t)(k0 + kk) * N + n0 + 4 * c4); if (gain) v = v * gain[k0 + kk];
;         *(LAS f32x4*)(scr + kk * 64 + 4 * (c4 ^ (2 * ((kk >> 3) & 7)))) = v; }
.LBB0_171:
	v_lshl_add_u64 v[130:131], v[64:65], 0, s[4:5]
	global_load_dwordx4 v[140:143], v[130:131], off
	v_lshl_add_u64 v[130:131], v[70:71], 0, s[4:5]
	global_load_dwordx4 v[144:147], v[130:131], off
	v_lshl_add_u64 v[130:131], v[66:67], 0, s[4:5]
	global_load_dwordx4 v[148:151], v[130:131], off
	v_lshl_add_u64 v[130:131], v[62:63], 0, s[4:5]
	global_load_dwordx4 v[152:155], v[130:131], off
	v_cndmask_b32_e64 v2, 0, 1, s[30:31]
	v_cmp_ne_u32_e64 s[0:1], 1, v2
	v_add_u32_e32 v136, s17, v12
	v_bitop3_b32 v132, v136, v11, 56 bitop3:0x6c
	v_lshl_add_u32 v132, v132, 2, v14
	v_add_u32_e32 v133, 4, v136
	v_bitop3_b32 v133, v133, v11, 56 bitop3:0x6c
	v_lshl_add_u32 v133, v133, 2, v14
	v_add_u32_e32 v134, 8, v136
	v_bitop3_b32 v134, v134, v11, 56 bitop3:0x6c
	v_lshl_add_u32 v134, v134, 2, v14
	v_add_u32_e32 v135, 12, v136
	v_bitop3_b32 v135, v135, v11, 56 bitop3:0x6c
	v_lshl_add_u32 v135, v135, 2, v14
	s_andn2_b64 vcc, exec, s[30:31]
	s_cbranch_vccnz .Ltrg6_nog
	global_load_dword v156, v[68:69], off offset:-32
	global_load_dword v158, v[68:69], off offset:-16
	global_load_dword v160, v[68:69], off
	global_load_dword v162, v[68:69], off offset:16
	s_waitcnt vmcnt(0)
	v_pk_mul_f32 v[142:143], v[142:143], v[156:157] op_sel_hi:[1,0]
	v_pk_mul_f32 v[140:141], v[140:141], v[156:157] op_sel_hi:[1,0]
	v_pk_mul_f32 v[146:147], v[146:147], v[158:159] op_sel_hi:[1,0]
	v_pk_mul_f32 v[144:145], v[144:145], v[158:159] op_sel_hi:[1,0]
	v_pk_mul_f32 v[150:151], v[150:151], v[160:161] op_sel_hi:[1,0]
	v_pk_mul_f32 v[148:149], v[148:149], v[160:161] op_sel_hi:[1,0]
	v_pk_mul_f32 v[154:155], v[154:155], v[162:163] op_sel_hi:[1,0]
	v_pk_mul_f32 v[152:153], v[152:153], v[162:163] op_sel_hi:[1,0]
	s_branch .Ltrg6_wr

; #define GAS __attribute__((address_space(1)))
; #define LAS __attribute__((address_space(3)))
; __device__ __forceinline__ void tr_item(const float* W, int K, int N, const float* gain, bf16* WT, int k0, int n0, int dstrow, LAS float* scr, int lane, float f8s) {
;     ...
; #pragma unroll 4
;     for (int i = 0; i < 16; ++i) { const int kk = 4 * i + r0; f32x4 v = *(const GAS f32x4*)(W + (size_t)(k0 + kk) * N + n0 + 4 * c4); if (gain) v = v * gain[k0 + kk];
;         *(LAS f32x4*)(scr + kk * 64 + 4 * (c4 ^ (2 * ((kk >> 3) & 7)))) = v; }
.LBB0_182:
	s_add_i32 s11, s11, 16
	v_add_u32_e32 v14, 0x1000, v14
	v_lshl_add_u64 v[62:63], v[62:63], 0, s[56:57]
	v_lshl_add_u64 v[64:65], v[64:65], 0, s[56:57]
	v_lshl_add_u64 v[66:67], v[66:67], 0, s[56:57]
	v_lshl_add_u64 v[68:69], v[68:69], 0, 64
	s_cmp_lg_u32 s11, 64
	v_lshl_add_u64 v[70:71], v[70:71], 0, s[56:57]
	s_cbranch_scc0 .LBB0_72
.LBB0_183:
	v_lshl_add_u64 v[130:131], v[64:65], 0, s[58:59]
	global_load_dwordx4 v[140:143], v[130:131], off
	v_lshl_add_u64 v[130:131], v[70:71], 0, s[58:59]
	global_load_dwordx4 v[144:147], v[130:131], off
	v_lshl_add_u64 v[130:131], v[66:67], 0, s[58:59]
	global_load_dwordx4 v[148:151], v[130:131], off
	v_lshl_add_u64 v[130:131], v[62:63], 0, s[58:59]
	global_load_dwordx4 v[152:155], v[130:131], off
	v_cndmask_b32_e64 v2, 0, 1, s[30:31]
	v_cmp_ne_u32_e64 s[0:1], 1, v2
	v_add_u32_e32 v136, s11, v12
	v_bitop3_b32 v132, v136, v11, 56 bitop3:0x6c
	v_lshl_add_u32 v132, v132, 2, v14
	v_add_u32_e32 v133, 4, v136
	v_bitop3_b32 v133, v133, v11, 56 bitop3:0x6c
	v_lshl_add_u32 v133, v133, 2, v14
	v_add_u32_e32 v134, 8, v136
	v_bitop3_b32 v134, v134, v11, 56 bitop3:0x6c
	v_lshl_add_u32 v134, v134, 2, v14
	v_add_u32_e32 v135, 12, v136
	v_bitop3_b32 v135, v135, v11, 56 bitop3:0x6c
	v_lshl_add_u32 v135, v135, 2, v14
	s_andn2_b64 vcc, exec, s[30:31]
	s_cbranch_vccnz .Ltrg7_nog
	global_load_dword v156, v[68:69], off offset:-32
	global_load_dword v158, v[68:69], off offset:-16
	global_load_dword v160, v[68:69], off
	global_load_dword v162, v[68:69], off offset:16
	s_waitcnt vmcnt(0)
	v_pk_mul_f32 v[142:143], v[142:143], v[156:157] op_sel_hi:[1,0]
	v_pk_mul_f32 v[140:141], v[140:141], v[156:157] op_sel_hi:[1,0]
	v_pk_mul_f32 v[146:147], v[146:147], v[158:159] op_sel_hi:[1,0]
	v_pk_mul_f32 v[144:145], v[144:145], v[158:159] op_sel_hi:[1,0]
	v_pk_mul_f32 v[150:151], v[150:151], v[160:161] op_sel_hi:[1,0]
	v_pk_mul_f32 v[148:149], v[148:149], v[160:161] op_sel_hi:[1,0]
	v_pk_mul_f32 v[154:155], v[154:155], v[162:163] op_sel_hi:[1,0]
	v_pk_mul_f32 v[152:153], v[152:153], v[162:163] op_sel_hi:[1,0]
	s_branch .Ltrg7_wr
